# GEMM k-loop heads (phase A both walks, phase E) aligned to 64 B with s_nop fill
# speedup vs baseline: 1.0135x; 1.0032x over previous
; DI void gemm_tile(const bf16_t* __restrict__ A, int lda, const bf16_t* __restrict__ Bt, int ldb, int bvalid, int K, f32x4 (&acc)[4][4], char* lds, bool preloaded = false) {
;   const int tid = tidx(), lane = tid & 63, wave = __builtin_amdgcn_readfirstlane(tid >> 6);
;   const int wm = wave >> 1, wn = wave & 1;
;   const int lr = tid >> 3, lc = tid & 7;
;   const int fr = lane & 15, fq = lane >> 4;
;   const int fx = (fr >> 1) & 7;
;   const bf16_t* ap = A + (size_t)lr * lda + ((lc ^ ((lr >> 1) & 7)) << 3);
;   const bf16_t* bp = Bt + ((lc ^ ((lr >> 1) & 7)) << 3);
;   typedef __attribute__((address_space(1))) const unsigned gptr_t;
;   typedef __attribute__((address_space(3))) unsigned lptr_t;
;   const unsigned lbase = (unsigned)(size_t)lds + (unsigned)tid * 16u;
;     ...
;   auto compute = [&](int st) {
;     const char* base = lds + st * 32768;
;     bf16x8 af[2][4], bfr[2][4];
; #pragma unroll
;     for (int s = 0; s < 2; ++s) {
;       const int ch = ((4 * s + fq) ^ fx) << 4;
; #pragma unroll
;       for (int mi = 0; mi < 4; ++mi) af[s][mi] = *(const bf16x8*)(base + (wm * 64 + mi * 16 + fr) * 128 + ch);
; #pragma unroll
;       for (int ni = 0; ni < 4; ++ni) bfr[s][ni] = *(const bf16x8*)(base + 16384 + (wn * 64 + ni * 16 + fr) * 128 + ch);
;     }
;     __builtin_amdgcn_s_setprio(1);
; #pragma unroll
;     for (int s = 0; s < 2; ++s)
; #pragma unroll
;       for (int mi = 0; mi < 4; ++mi)
; #pragma unroll
; DI void phaseE_tile(const P& p, int layer, int mt, int nt, char* lds) {
;   const int lane = tidx() & 63, wave = __builtin_amdgcn_readfirstlane(tidx() >> 6);
;   const int row0 = mt * 128, col0 = nt * 128;
;   const int wm = wave >> 1, wn = wave & 1, fr = lane & 15, fq = lane >> 4;
;   f32x4 acc[4][4];
;   zero_acc(acc);
;   float* XF = p.out;
;   const int col = col0 + wn * 64 + fr * 4;
;   f32x4 xr[16];
; #pragma unroll
;   for (int ps = 0; ps < 16; ++ps) {
;     const int row = row0 + ps * 8 + wm * 4 + fq;
;     const float* xin = (layer == 0) ? ((row < NTP) ? p.x_p + (size_t)row * DM : p.x_s + (size_t)(row - NTP) * DM) : XF + (size_t)row * DM;
;     xr[ps] = __builtin_nontemporal_load((const f32x4*)(xin + col));
;   }
;   gemm_tile((const bf16_t*)(p.ws + W_MERGED) + (size_t)row0 * LDX, LDX, (const bf16_t*)(p.ws + W_WO) + ((size_t)layer * 1024 + col0) * LDX, LDX, 128, 1024, acc, lds);
.LBB0_169:
	s_mul_i32 s8, s10, 0x880
	s_mul_hi_i32 s9, s10, 0x880
	s_add_u32 s24, s58, s8
	v_lshlrev_b64 v[62:63], 12, v[64:65]
	s_addc_u32 s25, s59, s9
	s_ashr_i32 s23, s22, 31
	v_lshl_add_u64 v[62:63], v[66:67], 0, v[62:63]
	s_add_u32 s26, s4, s22
	v_lshl_add_u64 v[62:63], v[130:131], 2, v[62:63]
	s_addc_u32 s23, s5, s23
	v_mov_b32_e32 v76, v158
	global_load_dwordx4 v[62:65], v[62:63], off nt
	s_mulk_i32 s23, 0x880
	s_mul_hi_u32 s27, s26, 0x880
	s_add_i32 s27, s27, s23
	v_lshrrev_b32_e32 v78, 4, v76
	s_mulk_i32 s26, 0x880
	v_readlane_b32 s28, v240, 31
	v_xor_b32_e32 v0, v78, v76
	v_readlane_b32 s29, v240, 32
	s_add_u32 s26, s28, s26
	v_ashrrev_i32_e32 v77, 3, v76
	v_mov_b64_e32 v[66:67], s[24:25]
	s_movk_i32 s28, 0x880
	v_lshlrev_b32_e32 v0, 4, v0
	s_addc_u32 s27, s29, s27
	v_mad_i64_i32 v[66:67], s[24:25], v77, s28, v[66:67]
	v_and_b32_e32 v0, 0x70, v0
	v_lshl_add_u64 v[66:67], v[66:67], 0, v[0:1]
	v_lshl_add_u64 v[68:69], s[26:27], 0, v[0:1]
	v_lshlrev_b32_e32 v145, 4, v76
	v_and_b32_e32 v0, 0x7f, v77
	v_add_u32_e32 v72, 0x4000, v145
	v_readfirstlane_b32 s24, v145
	v_mul_u32_u24_e32 v0, 0x440, v0
	s_mov_b32 m0, s24
	v_lshlrev_b32_e32 v0, 1, v0
	v_readfirstlane_b32 s24, v72
	global_load_lds_dwordx4 v[66:67], off
	v_lshl_add_u64 v[70:71], v[68:69], 0, v[0:1]
	s_mov_b32 m0, s24
	s_mov_b64 s[24:25], 0x11000
	v_add_u32_e32 v72, 0x1000, v145
	global_load_lds_dwordx4 v[70:71], off
	v_lshl_add_u64 v[70:71], v[66:67], 0, s[24:25]
	v_readfirstlane_b32 s24, v72
	s_mov_b32 m0, s24
	v_add_u32_e32 v74, 0x5000, v145
	global_load_lds_dwordx4 v[70:71], off
	v_add_u32_e32 v70, 32, v77
	v_and_b32_e32 v70, 0x7f, v70
	v_mul_u32_u24_e32 v70, 0x440, v70
	v_lshlrev_b32_e32 v70, 1, v70
	v_mov_b32_e32 v71, v1
	v_readfirstlane_b32 s24, v74
	v_lshl_add_u64 v[72:73], v[68:69], 0, v[70:71]
	s_mov_b32 m0, s24
	s_mov_b64 s[24:25], 0x22000
	v_add_u32_e32 v74, 0x2000, v145
	global_load_lds_dwordx4 v[72:73], off
	v_lshl_add_u64 v[72:73], v[66:67], 0, s[24:25]
	v_readfirstlane_b32 s24, v74
	s_mov_b32 m0, s24
	v_add_u32_e32 v82, 0x6000, v145
	global_load_lds_dwordx4 v[72:73], off
	v_bitop3_b32 v72, v77, 64, v166 bitop3:0x6c
	v_mul_u32_u24_e32 v72, 0x440, v72
	v_lshlrev_b32_e32 v72, 1, v72
	v_mov_b32_e32 v73, v1
	v_readfirstlane_b32 s24, v82
	v_lshl_add_u64 v[74:75], v[68:69], 0, v[72:73]
	s_mov_b32 m0, s24
	s_mov_b64 s[24:25], 0x33000
	global_load_lds_dwordx4 v[74:75], off
	v_add_u32_e32 v74, 0x3000, v145
	v_lshl_add_u64 v[66:67], v[66:67], 0, s[24:25]
	v_readfirstlane_b32 s24, v74
	s_mov_b32 m0, s24
	v_add_u32_e32 v74, 0x7000, v145
	global_load_lds_dwordx4 v[66:67], off
	v_add_u32_e32 v66, 0x60, v77
	v_and_b32_e32 v66, 0x7f, v66
	v_mul_u32_u24_e32 v66, 0x440, v66
	v_lshlrev_b32_e32 v66, 1, v66
	v_mov_b32_e32 v67, v1
	v_readfirstlane_b32 s24, v74
	v_lshl_add_u64 v[68:69], v[68:69], 0, v[66:67]
	s_mov_b32 m0, s24
	v_readfirstlane_b32 s23, v76
	global_load_lds_dwordx4 v[68:69], off
	s_lshl_b32 s24, s23, 7
	v_lshlrev_b32_e32 v68, 7, v76
	s_lshl_b32 s23, s23, 6
	v_bfe_u32 v79, v76, 4, 2
	v_lshrrev_b32_e32 v80, 1, v76
	v_bfe_u32 v81, v76, 1, 3
	s_and_b32 s24, s24, 0x2000
	v_and_b32_e32 v68, 0x780, v68
	s_and_b32 s23, s23, 0xffffe000
	v_or_b32_e32 v146, s24, v68
	v_bitop3_b32 v69, v80, v79, 7 bitop3:0x6c
	v_or_b32_e32 v148, s23, v68
	v_bitop3_b32 v68, v79, v81, 4 bitop3:0x36
	v_lshlrev_b32_e32 v149, 4, v69
	v_lshlrev_b32_e32 v147, 4, v68
	v_mov_b64_e32 v[68:69], s[8:9]
	v_bitop3_b32 v74, v78, 7, v76 bitop3:0x48
	v_mad_i64_i32 v[68:69], s[8:9], v77, s28, v[68:69]
	v_lshlrev_b32_e32 v74, 4, v74
	v_or_b32_e32 v68, v68, v74
	s_mul_hi_i32 s8, s22, 0x880
	s_mulk_i32 s22, 0x880
	v_lshl_add_u64 v[132:133], s[90:91], 0, v[68:69]
	v_or_b32_e32 v68, s22, v74
	v_mov_b32_e32 v69, s8
	v_lshl_add_u64 v[70:71], v[68:69], 0, v[70:71]
	v_lshl_add_u64 v[66:67], v[68:69], 0, v[66:67]
	v_lshl_add_u64 v[74:75], v[68:69], 0, v[0:1]
	v_lshl_add_u64 v[136:137], s[6:7], 0, v[70:71]
	v_lshl_add_u64 v[70:71], v[68:69], 0, v[72:73]
	v_lshl_add_u64 v[140:141], s[6:7], 0, v[66:67]
	v_mov_b32_e32 v66, 0
	v_lshl_add_u64 v[134:135], s[6:7], 0, v[74:75]
	v_lshl_add_u64 v[138:139], s[6:7], 0, v[70:71]
	s_mov_b64 s[8:9], 0
	s_mov_b32 s22, 0
	v_mov_b32_e32 v67, v66
	v_mov_b32_e32 v68, v66
	v_mov_b32_e32 v69, v66
	v_mov_b32_e32 v70, v66
	v_mov_b32_e32 v71, v66
	v_mov_b32_e32 v72, v66
	v_mov_b32_e32 v73, v66
	v_mov_b32_e32 v74, v66
	v_mov_b32_e32 v75, v66
	v_mov_b32_e32 v76, v66
	v_mov_b32_e32 v77, v66
	v_mov_b32_e32 v78, v66
	v_mov_b32_e32 v79, v66
	v_mov_b32_e32 v80, v66
	v_mov_b32_e32 v81, v66
	v_mov_b32_e32 v82, v66
	v_mov_b32_e32 v83, v66
	v_mov_b32_e32 v84, v66
	v_mov_b32_e32 v85, v66
	v_mov_b32_e32 v86, v66
	v_mov_b32_e32 v87, v66
	v_mov_b32_e32 v88, v66
	v_mov_b32_e32 v89, v66
	v_mov_b32_e32 v90, v66
	v_mov_b32_e32 v91, v66
	v_mov_b32_e32 v92, v66
	v_mov_b32_e32 v93, v66
	v_mov_b32_e32 v94, v66
	v_mov_b32_e32 v95, v66
	v_mov_b32_e32 v96, v66
	v_mov_b32_e32 v97, v66
	v_mov_b32_e32 v98, v66
	v_mov_b32_e32 v99, v66
	v_mov_b32_e32 v100, v66
	v_mov_b32_e32 v101, v66
	v_mov_b32_e32 v102, v66
	v_mov_b32_e32 v103, v66
	v_mov_b32_e32 v104, v66
	v_mov_b32_e32 v105, v66
	v_mov_b32_e32 v106, v66
	v_mov_b32_e32 v107, v66
	v_mov_b32_e32 v108, v66
	v_mov_b32_e32 v109, v66
	v_mov_b32_e32 v110, v66
	v_mov_b32_e32 v111, v66
	v_mov_b32_e32 v112, v66
	v_mov_b32_e32 v113, v66
	v_mov_b32_e32 v114, v66
	v_mov_b32_e32 v115, v66
	v_mov_b32_e32 v116, v66
	v_mov_b32_e32 v117, v66
	v_mov_b32_e32 v118, v66
	v_mov_b32_e32 v119, v66
	v_mov_b32_e32 v120, v66
	v_mov_b32_e32 v121, v66
	v_mov_b32_e32 v122, v66
	v_mov_b32_e32 v123, v66
	v_mov_b32_e32 v124, v66
	v_mov_b32_e32 v125, v66
	v_mov_b32_e32 v126, v66
	v_mov_b32_e32 v127, v66
	v_mov_b32_e32 v128, v66
	v_mov_b32_e32 v129, v66
	s_waitcnt vmcnt(0) lgkmcnt(0)
	s_barrier
	.p2alignl 6, 3212836864

; DI void gemm_tile(const bf16_t* __restrict__ A, int lda, const bf16_t* __restrict__ Bt, int ldb, int bvalid, int K, f32x4 (&acc)[4][4], char* lds, bool preloaded = false) {
;   const int tid = tidx(), lane = tid & 63, wave = __builtin_amdgcn_readfirstlane(tid >> 6);
;   const int wm = wave >> 1, wn = wave & 1;
;   const int lr = tid >> 3, lc = tid & 7;
;   const int fr = lane & 15, fq = lane >> 4;
;   const int fx = (fr >> 1) & 7;
;   const bf16_t* ap = A + (size_t)lr * lda + ((lc ^ ((lr >> 1) & 7)) << 3);
;   const bf16_t* bp = Bt + ((lc ^ ((lr >> 1) & 7)) << 3);
;   typedef __attribute__((address_space(1))) const unsigned gptr_t;
;   typedef __attribute__((address_space(3))) unsigned lptr_t;
;   const unsigned lbase = (unsigned)(size_t)lds + (unsigned)tid * 16u;
;     ...
;   auto compute = [&](int st) {
;     const char* base = lds + st * 32768;
;     bf16x8 af[2][4], bfr[2][4];
; #pragma unroll
;     for (int s = 0; s < 2; ++s) {
;       const int ch = ((4 * s + fq) ^ fx) << 4;
; #pragma unroll
;       for (int mi = 0; mi < 4; ++mi) af[s][mi] = *(const bf16x8*)(base + (wm * 64 + mi * 16 + fr) * 128 + ch);
; #pragma unroll
;       for (int ni = 0; ni < 4; ++ni) bfr[s][ni] = *(const bf16x8*)(base + 16384 + (wn * 64 + ni * 16 + fr) * 128 + ch);
;     }
;     __builtin_amdgcn_s_setprio(1);
; #pragma unroll
;     for (int s = 0; s < 2; ++s)
; #pragma unroll
;       for (int mi = 0; mi < 4; ++mi)
; #pragma unroll
;         for (int ni = 0; ni < 4; ++ni) acc[mi][ni] = MFMA16(af[s][mi], bfr[s][ni], acc[mi][ni]);
;     __builtin_amdgcn_s_setprio(0);
;   };
;   const int nk = K >> 6;
;   if (!preloaded) { GLDS(0, 0) }
; DI void phaseA_tile(const P& p, int layer, int mt, int nt, char* lds) {
;   const int tid = tidx(), lane = tid & 63, wave = __builtin_amdgcn_readfirstlane(tid >> 6);
;   const int row0 = mt * 128, col0 = nt * 128;
;   const int bvalid = (NP - col0) < 128 ? 64 : 128;
;   float* rr = (float*)(lds + RR_OFF);
;   __syncthreads();
;   const float* sp = (const float*)(p.ws + W_SS) + (size_t)(row0 + (tid & 127)) * 16;
;   const f32x4 ssa = *(const f32x4*)sp, ssb = *(const f32x4*)(sp + 4), ssc = *(const f32x4*)(sp + 8), ssd = *(const f32x4*)(sp + 12);
;   f32x4 acc[4][4];
;   zero_acc(acc);
;   gemm_tile((const bf16_t*)(p.ws + W_XB) + (size_t)row0 * DM, DM, (const bf16_t*)(p.ws + W_WIN) + ((size_t)layer * NP + col0) * 1024, 1024, bvalid, 1024, acc, lds);
.LBB0_1192:
	s_lshl_b32 s10, s36, 7
	s_ashr_i32 s11, s10, 31
	v_mov_b32_e32 v92, v158
	s_lshl_b32 s0, s37, 7
	s_lshl_b64 s[4:5], s[10:11], 11
	s_add_u32 s12, s74, s4
	v_and_b32_e32 v0, 0x7f, v92
	s_addc_u32 s13, s75, s5
	s_ashr_i32 s1, s0, 31
	v_or_b32_e32 v2, s10, v0
	s_add_u32 s14, s31, s0
	v_ashrrev_i32_e32 v3, 31, v2
	s_addc_u32 s15, s30, s1
	v_lshlrev_b64 v[2:3], 6, v[2:3]
	s_lshl_b64 s[14:15], s[14:15], 11
	v_lshl_add_u64 v[2:3], s[66:67], 0, v[2:3]
	v_mov_b32_e32 v16, v158
	s_add_u32 s14, s90, s14
	s_waitcnt vmcnt(63) expcnt(7) lgkmcnt(15)
	s_barrier
	global_load_dwordx4 v[66:69], v[2:3], off offset:48
	global_load_dwordx4 v[70:73], v[2:3], off offset:32
	global_load_dwordx4 v[74:77], v[2:3], off offset:16
	global_load_dwordx4 v[78:81], v[2:3], off
	s_addc_u32 s15, s91, s15
	v_ashrrev_i32_e32 v2, 3, v16
	v_lshrrev_b32_e32 v17, 4, v16
	v_ashrrev_i32_e32 v3, 31, v2
	v_xor_b32_e32 v0, v17, v16
	s_cmp_gt_i32 s37, 41
	v_lshlrev_b64 v[4:5], 11, v[2:3]
	v_lshlrev_b32_e32 v0, 4, v0
	v_lshl_add_u64 v[6:7], s[12:13], 0, v[4:5]
	v_and_b32_e32 v0, 0x70, v0
	v_lshlrev_b32_e32 v93, 4, v16
	s_cselect_b32 s12, 63, 0x7f
	v_lshl_add_u64 v[6:7], v[6:7], 0, v[0:1]
	v_lshl_add_u64 v[8:9], s[14:15], 0, v[0:1]
	v_add_u32_e32 v3, 0x4000, v93
	v_readfirstlane_b32 s13, v93
	v_and_b32_e32 v0, s12, v2
	s_mov_b32 m0, s13
	v_lshlrev_b32_e32 v0, 11, v0
	v_readfirstlane_b32 s13, v3
	v_add_u32_e32 v3, 0x1000, v93
	global_load_lds_dwordx4 v[6:7], off
	v_lshl_add_u64 v[10:11], v[8:9], 0, v[0:1]
	s_mov_b32 m0, s13
	s_mov_b64 s[14:15], 0x10000
	v_readfirstlane_b32 s13, v3
	v_add_u32_e32 v3, 32, v2
	global_load_lds_dwordx4 v[10:11], off
	v_lshl_add_u64 v[10:11], v[6:7], 0, s[14:15]
	s_mov_b32 m0, s13
	v_and_b32_e32 v3, s12, v3
	global_load_lds_dwordx4 v[10:11], off
	v_lshlrev_b32_e32 v10, 11, v3
	v_add_u32_e32 v3, 0x5000, v93
	v_mov_b32_e32 v11, v1
	v_readfirstlane_b32 s13, v3
	v_add_u32_e32 v3, 0x2000, v93
	v_lshl_add_u64 v[12:13], v[8:9], 0, v[10:11]
	s_mov_b32 m0, s13
	v_readfirstlane_b32 s13, v3
	global_load_lds_dwordx4 v[12:13], off
	v_lshl_add_u64 v[12:13], v[6:7], 0, s[60:61]
	s_mov_b32 m0, s13
	v_bitop3_b32 v3, v2, s12, 64 bitop3:0x48
	global_load_lds_dwordx4 v[12:13], off
	v_lshlrev_b32_e32 v12, 11, v3
	v_add_u32_e32 v3, 0x6000, v93
	v_mov_b32_e32 v13, v1
	v_readfirstlane_b32 s13, v3
	v_add_u32_e32 v3, 0x3000, v93
	v_add_u32_e32 v2, 0x60, v2
	v_lshl_add_u64 v[14:15], v[8:9], 0, v[12:13]
	s_mov_b32 m0, s13
	s_mov_b64 s[14:15], 0x30000
	v_readfirstlane_b32 s13, v3
	v_and_b32_e32 v2, s12, v2
	global_load_lds_dwordx4 v[14:15], off
	v_lshl_add_u64 v[6:7], v[6:7], 0, s[14:15]
	s_mov_b32 m0, s13
	v_lshlrev_b32_e32 v2, 11, v2
	v_mov_b32_e32 v3, v1
	global_load_lds_dwordx4 v[6:7], off
	v_lshl_add_u64 v[6:7], v[8:9], 0, v[2:3]
	v_add_u32_e32 v3, 0x7000, v93
	v_readfirstlane_b32 s11, v16
	v_readfirstlane_b32 s12, v3
	s_mov_b32 m0, s12
	s_lshl_b32 s12, s11, 7
	global_load_lds_dwordx4 v[6:7], off
	v_lshlrev_b32_e32 v3, 7, v16
	s_lshl_b32 s11, s11, 6
	v_bfe_u32 v18, v16, 4, 2
	v_bfe_u32 v20, v16, 1, 3
	s_and_b32 s12, s12, 0x2000
	v_and_b32_e32 v3, 0x780, v3
	s_and_b32 s11, s11, 0xffffe000
	v_or_b32_e32 v94, s12, v3
	v_or_b32_e32 v96, s11, v3
	v_bitop3_b32 v3, v18, v20, 4 bitop3:0x36
	v_lshlrev_b32_e32 v95, 4, v3
	v_bitop3_b32 v3, v17, 7, v16 bitop3:0x48
	v_lshlrev_b32_e32 v3, 4, v3
	v_or_b32_e32 v82, v4, v3
	s_lshl_b64 s[0:1], s[0:1], 11
	s_add_u32 s12, s74, s4
	s_addc_u32 s13, s75, s5
	v_readfirstlane_b32 s33, v93
	s_add_u32 s12, s12, 0x80
	s_addc_u32 s13, s13, 0
	v_add_u32_e32 v83, 0x10000, v82
	v_add_u32_e32 v84, 0x20000, v82
	v_add_u32_e32 v85, 0x30000, v82
	s_add_u32 s14, s2, s0
	s_addc_u32 s15, s3, s1
	v_or_b32_e32 v86, v0, v3
	v_or_b32_e32 v87, v10, v3
	v_lshrrev_b32_e32 v19, 1, v16
	v_or_b32_e32 v88, v12, v3
	v_bitop3_b32 v6, v19, v18, 7 bitop3:0x6c
	v_or_b32_e32 v89, v2, v3
	v_mov_b32_e32 v2, 0
	v_lshlrev_b32_e32 v97, 4, v6
	s_mov_b64 s[0:1], 0
	s_mov_b32 s4, 0
	v_mov_b32_e32 v3, 0
	v_mov_b64_e32 v[4:5], v[2:3]
	v_mov_b64_e32 v[6:7], v[2:3]
	v_mov_b64_e32 v[8:9], v[2:3]
	v_mov_b64_e32 v[10:11], v[2:3]
	v_mov_b64_e32 v[12:13], v[2:3]
	v_mov_b64_e32 v[14:15], v[2:3]
	v_mov_b64_e32 v[16:17], v[2:3]
	v_mov_b64_e32 v[18:19], v[2:3]
	v_mov_b64_e32 v[20:21], v[2:3]
	v_mov_b64_e32 v[22:23], v[2:3]
	v_mov_b64_e32 v[24:25], v[2:3]
	v_mov_b64_e32 v[26:27], v[2:3]
	v_mov_b64_e32 v[28:29], v[2:3]
	v_mov_b64_e32 v[30:31], v[2:3]
	v_mov_b64_e32 v[32:33], v[2:3]
	v_mov_b64_e32 v[34:35], v[2:3]
	v_mov_b64_e32 v[36:37], v[2:3]
	v_mov_b64_e32 v[38:39], v[2:3]
	v_mov_b64_e32 v[40:41], v[2:3]
	v_mov_b64_e32 v[42:43], v[2:3]
	v_mov_b64_e32 v[44:45], v[2:3]
	v_mov_b64_e32 v[46:47], v[2:3]
	v_mov_b64_e32 v[48:49], v[2:3]
	v_mov_b64_e32 v[50:51], v[2:3]
	v_mov_b64_e32 v[52:53], v[2:3]
	v_mov_b64_e32 v[54:55], v[2:3]
	v_mov_b64_e32 v[56:57], v[2:3]
	v_mov_b64_e32 v[58:59], v[2:3]
	v_mov_b64_e32 v[60:61], v[2:3]
	v_mov_b64_e32 v[62:63], v[2:3]
	v_mov_b64_e32 v[64:65], v[2:3]
	s_waitcnt vmcnt(0) lgkmcnt(0)
	s_barrier
	.p2alignl 6, 3212836864

; DI void gemm_tile(const bf16_t* __restrict__ A, int lda, const bf16_t* __restrict__ Bt, int ldb, int bvalid, int K, f32x4 (&acc)[4][4], char* lds, bool preloaded = false) {
;   const int tid = tidx(), lane = tid & 63, wave = __builtin_amdgcn_readfirstlane(tid >> 6);
;   const int wm = wave >> 1, wn = wave & 1;
;   const int lr = tid >> 3, lc = tid & 7;
;   const int fr = lane & 15, fq = lane >> 4;
;   const int fx = (fr >> 1) & 7;
;   const bf16_t* ap = A + (size_t)lr * lda + ((lc ^ ((lr >> 1) & 7)) << 3);
;   const bf16_t* bp = Bt + ((lc ^ ((lr >> 1) & 7)) << 3);
;   typedef __attribute__((address_space(1))) const unsigned gptr_t;
;   typedef __attribute__((address_space(3))) unsigned lptr_t;
;   const unsigned lbase = (unsigned)(size_t)lds + (unsigned)tid * 16u;
;     ...
;   auto compute = [&](int st) {
;     const char* base = lds + st * 32768;
;     bf16x8 af[2][4], bfr[2][4];
; #pragma unroll
;     for (int s = 0; s < 2; ++s) {
;       const int ch = ((4 * s + fq) ^ fx) << 4;
; #pragma unroll
;       for (int mi = 0; mi < 4; ++mi) af[s][mi] = *(const bf16x8*)(base + (wm * 64 + mi * 16 + fr) * 128 + ch);
; #pragma unroll
;       for (int ni = 0; ni < 4; ++ni) bfr[s][ni] = *(const bf16x8*)(base + 16384 + (wn * 64 + ni * 16 + fr) * 128 + ch);
;     }
;     __builtin_amdgcn_s_setprio(1);
; #pragma unroll
;     for (int s = 0; s < 2; ++s)
; #pragma unroll
;       for (int mi = 0; mi < 4; ++mi)
; #pragma unroll
;         for (int ni = 0; ni < 4; ++ni) acc[mi][ni] = MFMA16(af[s][mi], bfr[s][ni], acc[mi][ni]);
;     __builtin_amdgcn_s_setprio(0);
;   };
;   const int nk = K >> 6;
;   if (!preloaded) { GLDS(0, 0) }
; DI void phaseA_tile(const P& p, int layer, int mt, int nt, char* lds) {
;   const int tid = tidx(), lane = tid & 63, wave = __builtin_amdgcn_readfirstlane(tid >> 6);
;   const int row0 = mt * 128, col0 = nt * 128;
;   const int bvalid = (NP - col0) < 128 ? 64 : 128;
;   float* rr = (float*)(lds + RR_OFF);
;   __syncthreads();
;   const float* sp = (const float*)(p.ws + W_SS) + (size_t)(row0 + (tid & 127)) * 16;
;   const f32x4 ssa = *(const f32x4*)sp, ssb = *(const f32x4*)(sp + 4), ssc = *(const f32x4*)(sp + 8), ssd = *(const f32x4*)(sp + 12);
;   f32x4 acc[4][4];
;   zero_acc(acc);
;   gemm_tile((const bf16_t*)(p.ws + W_XB) + (size_t)row0 * DM, DM, (const bf16_t*)(p.ws + W_WIN) + ((size_t)layer * NP + col0) * 1024, 1024, bvalid, 1024, acc, lds);
.LBB0_1593:
	s_lshl_b32 s6, s36, 7
	s_ashr_i32 s7, s6, 31
	v_mov_b32_e32 v92, v158
	s_lshl_b32 s0, s37, 7
	s_lshl_b64 s[4:5], s[6:7], 11
	s_add_u32 s8, s74, s4
	v_and_b32_e32 v0, 0x7f, v92
	s_addc_u32 s9, s75, s5
	s_ashr_i32 s1, s0, 31
	v_or_b32_e32 v2, s6, v0
	s_add_u32 s10, s31, s0
	v_ashrrev_i32_e32 v3, 31, v2
	s_addc_u32 s11, s30, s1
	v_lshlrev_b64 v[2:3], 6, v[2:3]
	s_lshl_b64 s[10:11], s[10:11], 11
	v_lshl_add_u64 v[2:3], s[66:67], 0, v[2:3]
	v_mov_b32_e32 v16, v158
	s_add_u32 s10, s90, s10
	s_waitcnt vmcnt(63) expcnt(7) lgkmcnt(15)
	s_barrier
	global_load_dwordx4 v[66:69], v[2:3], off offset:48
	global_load_dwordx4 v[70:73], v[2:3], off offset:32
	global_load_dwordx4 v[74:77], v[2:3], off offset:16
	global_load_dwordx4 v[78:81], v[2:3], off
	s_addc_u32 s11, s91, s11
	v_ashrrev_i32_e32 v2, 3, v16
	v_lshrrev_b32_e32 v17, 4, v16
	v_ashrrev_i32_e32 v3, 31, v2
	v_xor_b32_e32 v0, v17, v16
	s_cmp_gt_i32 s37, 41
	v_lshlrev_b64 v[4:5], 11, v[2:3]
	v_lshlrev_b32_e32 v0, 4, v0
	v_lshl_add_u64 v[6:7], s[8:9], 0, v[4:5]
	v_and_b32_e32 v0, 0x70, v0
	v_lshlrev_b32_e32 v93, 4, v16
	s_cselect_b32 s8, 63, 0x7f
	v_lshl_add_u64 v[6:7], v[6:7], 0, v[0:1]
	v_lshl_add_u64 v[8:9], s[10:11], 0, v[0:1]
	v_add_u32_e32 v3, 0x4000, v93
	v_readfirstlane_b32 s9, v93
	v_and_b32_e32 v0, s8, v2
	s_mov_b32 m0, s9
	v_lshlrev_b32_e32 v0, 11, v0
	v_readfirstlane_b32 s9, v3
	v_add_u32_e32 v3, 0x1000, v93
	global_load_lds_dwordx4 v[6:7], off
	v_lshl_add_u64 v[10:11], v[8:9], 0, v[0:1]
	s_mov_b32 m0, s9
	s_mov_b64 s[10:11], 0x10000
	v_readfirstlane_b32 s9, v3
	v_add_u32_e32 v3, 32, v2
	global_load_lds_dwordx4 v[10:11], off
	v_lshl_add_u64 v[10:11], v[6:7], 0, s[10:11]
	s_mov_b32 m0, s9
	v_and_b32_e32 v3, s8, v3
	global_load_lds_dwordx4 v[10:11], off
	v_lshlrev_b32_e32 v10, 11, v3
	v_add_u32_e32 v3, 0x5000, v93
	v_mov_b32_e32 v11, v1
	v_readfirstlane_b32 s9, v3
	v_add_u32_e32 v3, 0x2000, v93
	v_lshl_add_u64 v[12:13], v[8:9], 0, v[10:11]
	s_mov_b32 m0, s9
	v_readfirstlane_b32 s9, v3
	global_load_lds_dwordx4 v[12:13], off
	v_lshl_add_u64 v[12:13], v[6:7], 0, s[60:61]
	s_mov_b32 m0, s9
	v_bitop3_b32 v3, v2, s8, 64 bitop3:0x48
	global_load_lds_dwordx4 v[12:13], off
	v_lshlrev_b32_e32 v12, 11, v3
	v_add_u32_e32 v3, 0x6000, v93
	v_mov_b32_e32 v13, v1
	v_readfirstlane_b32 s9, v3
	v_add_u32_e32 v3, 0x3000, v93
	v_add_u32_e32 v2, 0x60, v2
	v_lshl_add_u64 v[14:15], v[8:9], 0, v[12:13]
	s_mov_b32 m0, s9
	s_mov_b64 s[10:11], 0x30000
	v_readfirstlane_b32 s9, v3
	v_and_b32_e32 v2, s8, v2
	global_load_lds_dwordx4 v[14:15], off
	v_lshl_add_u64 v[6:7], v[6:7], 0, s[10:11]
	s_mov_b32 m0, s9
	v_lshlrev_b32_e32 v2, 11, v2
	v_mov_b32_e32 v3, v1
	global_load_lds_dwordx4 v[6:7], off
	v_lshl_add_u64 v[6:7], v[8:9], 0, v[2:3]
	v_add_u32_e32 v3, 0x7000, v93
	v_readfirstlane_b32 s7, v16
	v_readfirstlane_b32 s8, v3
	s_mov_b32 m0, s8
	s_lshl_b32 s8, s7, 7
	global_load_lds_dwordx4 v[6:7], off
	v_lshlrev_b32_e32 v3, 7, v16
	s_lshl_b32 s7, s7, 6
	v_bfe_u32 v18, v16, 4, 2
	v_bfe_u32 v20, v16, 1, 3
	s_and_b32 s8, s8, 0x2000
	v_and_b32_e32 v3, 0x780, v3
	s_and_b32 s7, s7, 0xffffe000
	v_or_b32_e32 v94, s8, v3
	v_or_b32_e32 v96, s7, v3
	v_bitop3_b32 v3, v18, v20, 4 bitop3:0x36
	v_lshlrev_b32_e32 v95, 4, v3
	v_bitop3_b32 v3, v17, 7, v16 bitop3:0x48
	v_lshl_add_u64 v[4:5], v[4:5], 0, s[4:5]
	v_lshlrev_b32_e32 v3, 4, v3
	v_or_b32_e32 v4, v4, v3
	s_lshl_b64 s[0:1], s[0:1], 11
	v_lshl_add_u64 v[82:83], s[90:91], 0, v[4:5]
	v_or3_b32 v4, s0, v0, v3
	v_mov_b32_e32 v5, s1
	v_lshl_add_u64 v[84:85], s[2:3], 0, v[4:5]
	v_or3_b32 v4, s0, v10, v3
	v_lshrrev_b32_e32 v19, 1, v16
	v_lshl_add_u64 v[86:87], s[2:3], 0, v[4:5]
	v_or3_b32 v4, s0, v12, v3
	v_bitop3_b32 v6, v19, v18, 7 bitop3:0x6c
	v_lshl_add_u64 v[88:89], s[2:3], 0, v[4:5]
	v_or3_b32 v4, s0, v2, v3
	v_mov_b32_e32 v2, 0
	v_lshlrev_b32_e32 v97, 4, v6
	v_lshl_add_u64 v[90:91], s[2:3], 0, v[4:5]
	s_mov_b64 s[0:1], 0
	s_mov_b32 s4, 0
	v_mov_b32_e32 v3, v2
	v_mov_b32_e32 v4, v2
	v_mov_b32_e32 v5, v2
	v_mov_b32_e32 v6, v2
	v_mov_b32_e32 v7, v2
	v_mov_b32_e32 v8, v2
	v_mov_b32_e32 v9, v2
	v_mov_b32_e32 v10, v2
	v_mov_b32_e32 v11, v2
	v_mov_b32_e32 v12, v2
	v_mov_b32_e32 v13, v2
	v_mov_b32_e32 v14, v2
	v_mov_b32_e32 v15, v2
	v_mov_b32_e32 v16, v2
	v_mov_b32_e32 v17, v2
	v_mov_b32_e32 v18, v2
	v_mov_b32_e32 v19, v2
	v_mov_b32_e32 v20, v2
	v_mov_b32_e32 v21, v2
	v_mov_b32_e32 v22, v2
	v_mov_b32_e32 v23, v2
	v_mov_b32_e32 v24, v2
	v_mov_b32_e32 v25, v2
	v_mov_b32_e32 v26, v2
	v_mov_b32_e32 v27, v2
	v_mov_b32_e32 v28, v2
	v_mov_b32_e32 v29, v2
	v_mov_b32_e32 v30, v2
	v_mov_b32_e32 v31, v2
	v_mov_b32_e32 v32, v2
	v_mov_b32_e32 v33, v2
	v_mov_b32_e32 v34, v2
	v_mov_b32_e32 v35, v2
	v_mov_b32_e32 v36, v2
	v_mov_b32_e32 v37, v2
	v_mov_b32_e32 v38, v2
	v_mov_b32_e32 v39, v2
	v_mov_b32_e32 v40, v2
	v_mov_b32_e32 v41, v2
	v_mov_b32_e32 v42, v2
	v_mov_b32_e32 v43, v2
	v_mov_b32_e32 v44, v2
	v_mov_b32_e32 v45, v2
	v_mov_b32_e32 v46, v2
	v_mov_b32_e32 v47, v2
	v_mov_b32_e32 v48, v2
	v_mov_b32_e32 v49, v2
	v_mov_b32_e32 v50, v2
	v_mov_b32_e32 v51, v2
	v_mov_b32_e32 v52, v2
	v_mov_b32_e32 v53, v2
	v_mov_b32_e32 v54, v2
	v_mov_b32_e32 v55, v2
	v_mov_b32_e32 v56, v2
	v_mov_b32_e32 v57, v2
	v_mov_b32_e32 v58, v2
	v_mov_b32_e32 v59, v2
	v_mov_b32_e32 v60, v2
	v_mov_b32_e32 v61, v2
	v_mov_b32_e32 v62, v2
	v_mov_b32_e32 v63, v2
	v_mov_b32_e32 v64, v2
	v_mov_b32_e32 v65, v2
	s_mov_b64 s[8:9], 0x1f46080
	s_mov_b64 s[10:11], 0x1f56080
	s_mov_b64 s[12:13], 0x1f66080
	s_mov_b64 s[14:15], 0x1f76080
	s_waitcnt vmcnt(0) lgkmcnt(0)
	s_barrier
	.p2alignl 6, 3212836864
